# attention hot heads: 3 unnecessary s_nop around the permlane removed per tile, duplicate V-address add shared between head and body
# baseline (speedup 1.0000x reference)
.Lattn1_nomask:
	s_add_i32 s9, s78, 0x10000
	s_and_b32 s33, s9, 0x18000
	s_and_b32 s76, s78, 0x18000
	v_add_u32_e32 v239, s33, v237
	v_add_u32_e32 v250, v239, v228
	ds_read_b128 v[128:131], v250 offset:16384
	ds_read_b128 v[132:135], v250 offset:20480
	ds_read_b128 v[136:139], v250 offset:24576
	ds_read_b128 v[140:143], v250 offset:28672
	v_add_u32_e32 v251, s76, v235
	v_add_u32_e32 v250, v251, v228
	ds_read_b128 v[144:147], v250
	ds_read_b128 v[148:151], v250 offset:4096
	v_add_u32_e32 v250, v251, v231
	ds_read_b128 v[152:155], v250
	ds_read_b128 v[156:159], v250 offset:4096
	s_add_i32 s0, s74, s38
	s_addk_i32 s0, 0xc0
	s_mul_i32 s0, s0, s14
	s_lshl_b32 s92, s46, 1
	s_add_i32 s0, s0, s92
	s_addk_i32 s0, 0x1c00
	s_add_u32 s98, s82, s0
	s_addc_u32 s99, s83, 0
	s_add_i32 s0, s78, 0x8000
	s_and_b32 s0, s0, 0x18000
	s_add_i32 s0, s5, s0
	s_mov_b32 m0, s0
	s_nop 0
	global_load_lds_dwordx4 v244, s[98:99]
	s_add_i32 m0, s0, 0x2000
	s_add_u32 s98, s98, 0x80
	s_addc_u32 s99, s99, 0
	global_load_lds_dwordx4 v244, s[98:99]
	s_lshl_b32 s1, s17, 13
	s_add_u32 s98, s40, s1
	s_addc_u32 s99, s41, 0
	s_add_i32 m0, s0, 0x4000
	s_nop 0
	global_load_lds_dwordx4 v245, s[98:99]
	s_add_i32 m0, s0, 0x6000
	s_add_u32 s98, s98, 0x80000
	s_addc_u32 s99, s99, 0
	global_load_lds_dwordx4 v245, s[98:99]
	v_max3_f32 v246, v64, v65, v66
	v_max3_f32 v247, v72, v73, v74
	v_max3_f32 v248, v80, v81, v82
	v_max3_f32 v249, v88, v89, v90
	v_max3_f32 v246, v246, v67, v68
	v_max3_f32 v247, v247, v75, v76
	v_max3_f32 v248, v248, v83, v84
	v_max3_f32 v249, v249, v91, v92
	s_waitcnt lgkmcnt(7)
	v_mfma_f32_32x32x16_bf16 v[0:15], v[128:131], v[96:99], v[0:15]
	v_max3_f32 v246, v246, v69, v70
	v_max3_f32 v247, v247, v77, v78
	v_max3_f32 v248, v248, v85, v86
	v_max3_f32 v249, v249, v93, v94
	v_max3_f32 v246, v246, v71, v247
	v_max3_f32 v247, v248, v87, v249
	s_waitcnt lgkmcnt(6)
	v_mfma_f32_32x32x16_bf16 v[48:63], v[132:135], v[96:99], v[48:63]
	v_max3_f32 v246, v246, v79, v95
	v_max3_f32 v246, v246, v247, v247
	v_mov_b32_e32 v247, v246
	s_nop 1
	v_permlane32_swap_b32_e32 v246, v247
	v_max3_f32 v246, v246, v247, v247
	v_max_f32_e32 v251, v212, v246
	s_waitcnt lgkmcnt(5)
	v_mfma_f32_32x32x16_bf16 v[32:47], v[136:139], v[96:99], v[32:47]
	v_sub_f32_e32 v247, v212, v251
	v_exp_f32_e32 v250, v247
	v_add_f32_e32 v247, 0x41000000, v212
	v_cmp_gt_f32_e32 vcc, v246, v247
	s_cmp_eq_u64 vcc, 0
	v_mul_f32_e32 v246, v100, v250
	s_cselect_b64 s[0:1], -1, 0
	v_cndmask_b32_e64 v194, v246, v100, s[0:1]
	s_waitcnt lgkmcnt(4)
	v_mfma_f32_32x32x16_bf16 v[16:31], v[140:143], v[96:99], v[16:31]
	v_cndmask_b32_e64 v212, v251, v212, s[0:1]
	v_sub_f32_e32 v140, v92, v212
	v_sub_f32_e32 v141, v93, v212
	v_sub_f32_e32 v138, v90, v212
	v_sub_f32_e32 v139, v91, v212
	s_waitcnt lgkmcnt(3)
	v_mfma_f32_32x32x16_bf16 v[96:111], v[144:147], v[160:163], 0
	v_sub_f32_e32 v142, v94, v212
	v_sub_f32_e32 v143, v95, v212
	v_sub_f32_e32 v92, v80, v212
	v_sub_f32_e32 v93, v81, v212
	v_sub_f32_e32 v128, v82, v212
	v_sub_f32_e32 v129, v83, v212
	s_waitcnt lgkmcnt(2)
	v_mfma_f32_32x32x16_bf16 v[112:127], v[148:151], v[160:163], 0
	v_sub_f32_e32 v130, v68, v212
	v_sub_f32_e32 v131, v69, v212
	v_sub_f32_e32 v90, v64, v212
	v_sub_f32_e32 v91, v65, v212
	v_sub_f32_e32 v132, v84, v212
	v_sub_f32_e32 v133, v85, v212
	s_waitcnt lgkmcnt(1)
	v_mfma_f32_32x32x16_bf16 v[96:111], v[152:155], v[164:167], v[96:111]
	v_sub_f32_e32 v94, v66, v212
	v_sub_f32_e32 v95, v67, v212
	v_sub_f32_e32 v134, v86, v212
	v_sub_f32_e32 v135, v87, v212
	v_sub_f32_e32 v136, v88, v212
	v_sub_f32_e32 v137, v89, v212
	s_waitcnt lgkmcnt(0)
	v_mfma_f32_32x32x16_bf16 v[112:127], v[156:159], v[164:167], v[112:127]
	v_sub_f32_e32 v144, v70, v212
	v_sub_f32_e32 v145, v71, v212
	v_sub_f32_e32 v148, v74, v212
	v_sub_f32_e32 v149, v75, v212
	v_sub_f32_e32 v150, v76, v212
	v_sub_f32_e32 v151, v77, v212
	v_sub_f32_e32 v146, v72, v212
	v_sub_f32_e32 v147, v73, v212
	v_sub_f32_e32 v152, v78, v212
	v_sub_f32_e32 v153, v79, v212
	v_mov_b32_e32 v68, v250
	s_branch .Lattn_body_1
.LBB0_834:
	v_max3_f32 v64, v144, v145, v146
	v_max3_f32 v65, v152, v153, v154
	v_max3_f32 v66, v128, v129, v130
	v_max3_f32 v67, v136, v137, v138
	s_add_i32 s9, s78, 0x10000
	v_max3_f32 v64, v64, v147, v148
	v_max3_f32 v65, v65, v155, v156
	v_max3_f32 v66, v66, v131, v132
	v_max3_f32 v67, v67, v139, v140
	s_and_b32 s33, s9, 0x18000
	v_max3_f32 v64, v64, v149, v150
	v_max3_f32 v65, v65, v157, v158
	v_max3_f32 v66, v66, v133, v134
	v_max3_f32 v67, v67, v141, v142
	s_and_b32 s76, s78, 0x18000
	v_max3_f32 v64, v64, v151, v65
	v_max3_f32 v65, v66, v135, v67
	v_max_f32_e32 v66, v212, v212
	v_max3_f32 v64, v64, v159, v143
	s_nop 0
	v_max3_f32 v64, v64, v65, v65
	s_nop 0
	v_mov_b32_e32 v65, v64
	s_nop 1
	v_permlane32_swap_b32_e32 v64, v65
	v_max3_f32 v64, v64, v65, v65
	s_nop 0
	v_max_f32_e32 v65, v64, v64
	v_max_f32_e32 v69, v66, v65
	v_sub_f32_e32 v65, v212, v69
	v_exp_f32_e32 v68, v65
	v_add_f32_e32 v65, 0x41000000, v212
	v_cmp_gt_f32_e32 vcc, v64, v65
	s_cmp_eq_u64 vcc, 0
	v_mul_f32_e32 v64, v100, v68
	s_cselect_b64 s[0:1], -1, 0
	v_cndmask_b32_e64 v194, v64, v100, s[0:1]
	v_cndmask_b32_e64 v212, v69, v212, s[0:1]
	v_mov_b32_e32 v213, v212
	v_sub_f32_e32 v92, v128, v212
	v_sub_f32_e32 v93, v129, v213
	v_sub_f32_e32 v128, v130, v212
	v_sub_f32_e32 v129, v131, v213
	v_sub_f32_e32 v130, v148, v212
	v_sub_f32_e32 v131, v149, v213
	v_sub_f32_e32 v90, v144, v212
	v_sub_f32_e32 v91, v145, v213
	v_sub_f32_e32 v132, v132, v212
	v_sub_f32_e32 v133, v133, v213
	v_sub_f32_e32 v144, v150, v212
	v_sub_f32_e32 v145, v151, v213
	v_sub_f32_e32 v148, v154, v212
	v_sub_f32_e32 v149, v155, v213
	v_sub_f32_e32 v150, v156, v212
	v_sub_f32_e32 v151, v157, v213
	v_sub_f32_e32 v140, v140, v212
	v_sub_f32_e32 v141, v141, v213
	v_sub_f32_e32 v138, v138, v212
	v_sub_f32_e32 v139, v139, v213
	v_sub_f32_e32 v94, v146, v212
	v_sub_f32_e32 v95, v147, v213
	v_sub_f32_e32 v146, v152, v212
	v_sub_f32_e32 v147, v153, v213
	v_sub_f32_e32 v152, v158, v212
	v_sub_f32_e32 v153, v159, v213
	v_sub_f32_e32 v142, v142, v212
	v_sub_f32_e32 v143, v143, v213
	v_sub_f32_e32 v134, v134, v212
	v_sub_f32_e32 v135, v135, v213
	v_sub_f32_e32 v136, v136, v212
	v_sub_f32_e32 v137, v137, v213
	v_add_u32_e32 v74, s33, v237
	v_add_u32_e32 v74, v74, v228
	ds_read_b128 v[64:67], v74 offset:16384
	ds_read_b128 v[70:73], v74 offset:20480
	s_waitcnt lgkmcnt(0)
	v_mfma_f32_32x32x16_bf16 v[0:15], v[64:67], v[96:99], v[0:15]
	v_mfma_f32_32x32x16_bf16 v[48:63], v[70:73], v[96:99], v[48:63]
	ds_read_b128 v[64:67], v74 offset:24576
	ds_read_b128 v[70:73], v74 offset:28672
	s_waitcnt lgkmcnt(0)
	v_mfma_f32_32x32x16_bf16 v[32:47], v[64:67], v[96:99], v[32:47]
	v_mfma_f32_32x32x16_bf16 v[16:31], v[70:73], v[96:99], v[16:31]
	v_add_u32_e32 v74, s76, v235
	v_add_u32_e32 v74, v74, v228
	ds_read_b128 v[64:67], v74
	ds_read_b128 v[70:73], v74 offset:4096
	v_add_u32_e32 v74, s76, v235
	v_add_u32_e32 v74, v74, v231
	s_waitcnt lgkmcnt(0)
	v_mfma_f32_32x32x16_bf16 v[96:111], v[64:67], v[160:163], 0
	ds_read_b128 v[64:67], v74
	ds_read_b128 v[74:77], v74 offset:4096
	v_mfma_f32_32x32x16_bf16 v[112:127], v[70:73], v[160:163], 0
	s_waitcnt lgkmcnt(0)
	v_mfma_f32_32x32x16_bf16 v[96:111], v[64:67], v[164:167], v[96:111]
	v_mfma_f32_32x32x16_bf16 v[112:127], v[74:77], v[164:167], v[112:127]
	v_add_u32_e32 v239, s33, v237
.Lattn_body_1:
	v_add_u32_e32 v86, s76, v235
	v_add_u32_e32 v78, v239, v231
	v_add_u32_e32 v82, v86, v230
	v_add_u32_e32 v69, v239, v230
	v_exp_f32_e32 v130, v130
	v_exp_f32_e32 v154, v132
	v_exp_f32_e32 v131, v131
	v_exp_f32_e32 v155, v133
	v_add_u32_e32 v86, v86, v229
	v_exp_f32_e32 v158, v138
	v_exp_f32_e32 v159, v139
	v_exp_f32_e32 v94, v94
	v_exp_f32_e32 v128, v128
	v_exp_f32_e32 v95, v95
	v_exp_f32_e32 v129, v129
	v_exp_f32_e32 v132, v144
	v_exp_f32_e32 v144, v134
	v_exp_f32_e32 v133, v145
	v_exp_f32_e32 v145, v135
	v_exp_f32_e32 v148, v148
	v_exp_f32_e32 v149, v149
	v_exp_f32_e32 v142, v142
	v_exp_f32_e32 v143, v143
	ds_read_b128 v[64:67], v78 offset:16384
	ds_read_b128 v[70:73], v78 offset:20480
	v_exp_f32_e32 v90, v90
	v_exp_f32_e32 v92, v92
	v_exp_f32_e32 v91, v91
	v_exp_f32_e32 v93, v93
	v_exp_f32_e32 v146, v146
	v_exp_f32_e32 v156, v136
	v_exp_f32_e32 v147, v147
	v_exp_f32_e32 v157, v137
	v_add_f32_e32 v136, v90, v92
	v_add_f32_e32 v137, v91, v93
	s_waitcnt lgkmcnt(0)
	v_mfma_f32_32x32x16_bf16 v[0:15], v[64:67], v[184:187], v[0:15]
	ds_read_b128 v[64:67], v78 offset:24576
	ds_read_b128 v[74:77], v78 offset:28672
	ds_read_b128 v[78:81], v82
	ds_read_b128 v[82:85], v82 offset:4096
	v_mfma_f32_32x32x16_bf16 v[48:63], v[70:73], v[184:187], v[48:63]
	ds_read_b128 v[70:73], v86
	ds_read_b128 v[86:89], v86 offset:4096
	s_waitcnt lgkmcnt(0)
	v_mfma_f32_32x32x16_bf16 v[32:47], v[64:67], v[184:187], v[32:47]
	ds_read_b128 v[64:67], v69 offset:16384
	v_mfma_f32_32x32x16_bf16 v[16:31], v[74:77], v[184:187], v[16:31]
	ds_read_b128 v[74:77], v69 offset:20480
	s_waitcnt lgkmcnt(0)
	v_mfma_f32_32x32x16_bf16 v[0:15], v[64:67], v[180:183], v[0:15]
	ds_read_b128 v[64:67], v69 offset:24576
	v_mfma_f32_32x32x16_bf16 v[96:111], v[78:81], v[168:171], v[96:111]
	v_exp_f32_e32 v78, v150
	v_exp_f32_e32 v80, v140
	v_exp_f32_e32 v79, v151
	v_exp_f32_e32 v81, v141
	v_exp_f32_e32 v150, v152
	v_exp_f32_e32 v151, v153
	v_mfma_f32_32x32x16_bf16 v[48:63], v[74:77], v[180:183], v[48:63]
	ds_read_b128 v[74:77], v69 offset:28672
	v_add_u32_e32 v69, v239, v229
	v_add_f32_e64 v134, v150, v142
	v_add_f32_e64 v135, v151, v143
	s_waitcnt lgkmcnt(0)
	v_mfma_f32_32x32x16_bf16 v[32:47], v[64:67], v[180:183], v[32:47]
	ds_read_b128 v[64:67], v69 offset:16384
	v_mfma_f32_32x32x16_bf16 v[96:111], v[70:73], v[172:175], v[96:111]
	v_add_f32_e64 v70, v78, v80
	v_add_f32_e64 v71, v79, v81
	v_add_f32_e64 v72, v130, v154
	v_add_f32_e64 v73, v131, v155
	v_add_f32_e64 v138, v72, v70
	v_add_f32_e64 v139, v73, v71
	ds_read_b128 v[70:73], v69 offset:20480
	v_mfma_f32_32x32x16_bf16 v[16:31], v[74:77], v[180:183], v[16:31]
	v_add_f32_e64 v74, v148, v158
	v_add_f32_e64 v75, v149, v159
	v_add_f32_e64 v76, v94, v128
	v_add_f32_e64 v77, v95, v129
	v_add_f32_e64 v74, v76, v74
	v_add_f32_e64 v75, v77, v75
	v_mfma_f32_32x32x16_bf16 v[112:127], v[82:85], v[168:171], v[112:127]
	v_add_f32_e64 v82, v132, v144
	v_add_f32_e64 v83, v133, v145
	v_add_f32_e64 v84, v146, v156
	v_add_f32_e64 v85, v147, v157
	s_waitcnt lgkmcnt(0)
	v_mfma_f32_32x32x16_bf16 v[0:15], v[64:67], v[176:179], v[0:15]
	v_add_f32_e64 v66, v82, v134
	v_add_f32_e64 v67, v83, v135
	v_add_f32_e64 v64, v136, v84
	v_add_f32_e64 v65, v137, v85
	v_add_f32_e64 v66, v74, v66
	v_add_f32_e64 v67, v75, v67
	ds_read_b128 v[74:77], v69 offset:24576
	v_add_f32_e32 v64, v64, v138
	v_add_f32_e32 v65, v65, v139
	v_cvt_pk_bf16_f32 v134, v154, v155
	v_add_f32_e32 v64, v64, v65
	v_mfma_f32_32x32x16_bf16 v[48:63], v[70:73], v[176:179], v[48:63]
	ds_read_b128 v[70:73], v69 offset:28672
	v_add_f32_e32 v65, v66, v67
	v_add_f32_e32 v82, v64, v65
	v_cvt_pk_bf16_f32 v64, v90, v91
	v_cvt_pk_bf16_f32 v65, v94, v95
	v_cvt_pk_bf16_f32 v66, v130, v131
	v_cvt_pk_bf16_f32 v67, v132, v133
	s_waitcnt lgkmcnt(0)
	v_mfma_f32_32x32x16_bf16 v[32:47], v[74:77], v[176:179], v[32:47]
	v_cvt_pk_bf16_f32 v132, v92, v93
	v_cvt_pk_bf16_f32 v133, v128, v129
	v_cvt_pk_bf16_f32 v135, v144, v145
	v_cvt_pk_bf16_f32 v136, v146, v147
	v_cvt_pk_bf16_f32 v137, v148, v149
	v_cvt_pk_bf16_f32 v138, v78, v79
	v_cvt_pk_bf16_f32 v139, v150, v151
	v_mfma_f32_32x32x16_bf16 v[16:31], v[70:73], v[176:179], v[16:31]
	v_cvt_pk_bf16_f32 v128, v156, v157
	v_cvt_pk_bf16_f32 v129, v158, v159
	v_cvt_pk_bf16_f32 v130, v80, v81
	v_cvt_pk_bf16_f32 v131, v142, v143
	v_add_f32_e32 v69, v194, v82
	v_mfma_f32_32x32x16_bf16 v[112:127], v[86:89], v[172:175], v[112:127]
	s_cbranch_vccz .LBB0_836
	v_pk_mul_f32 v[14:15], v[68:69], v[14:15] op_sel_hi:[0,1]
	v_pk_mul_f32 v[12:13], v[68:69], v[12:13] op_sel_hi:[0,1]
	v_pk_mul_f32 v[10:11], v[68:69], v[10:11] op_sel_hi:[0,1]
	v_pk_mul_f32 v[8:9], v[68:69], v[8:9] op_sel_hi:[0,1]
	v_pk_mul_f32 v[6:7], v[68:69], v[6:7] op_sel_hi:[0,1]
	v_pk_mul_f32 v[4:5], v[68:69], v[4:5] op_sel_hi:[0,1]
	v_pk_mul_f32 v[2:3], v[68:69], v[2:3] op_sel_hi:[0,1]
	v_pk_mul_f32 v[0:1], v[68:69], v[0:1] op_sel_hi:[0,1]
	v_pk_mul_f32 v[62:63], v[68:69], v[62:63] op_sel_hi:[0,1]
	v_pk_mul_f32 v[60:61], v[68:69], v[60:61] op_sel_hi:[0,1]
	v_pk_mul_f32 v[58:59], v[68:69], v[58:59] op_sel_hi:[0,1]
	v_pk_mul_f32 v[56:57], v[68:69], v[56:57] op_sel_hi:[0,1]
	v_pk_mul_f32 v[54:55], v[68:69], v[54:55] op_sel_hi:[0,1]
	v_pk_mul_f32 v[52:53], v[68:69], v[52:53] op_sel_hi:[0,1]
	v_pk_mul_f32 v[50:51], v[68:69], v[50:51] op_sel_hi:[0,1]
	v_pk_mul_f32 v[48:49], v[68:69], v[48:49] op_sel_hi:[0,1]
	v_pk_mul_f32 v[46:47], v[68:69], v[46:47] op_sel_hi:[0,1]
	v_pk_mul_f32 v[44:45], v[68:69], v[44:45] op_sel_hi:[0,1]
	v_pk_mul_f32 v[42:43], v[68:69], v[42:43] op_sel_hi:[0,1]
	v_pk_mul_f32 v[40:41], v[68:69], v[40:41] op_sel_hi:[0,1]
	v_pk_mul_f32 v[38:39], v[68:69], v[38:39] op_sel_hi:[0,1]
	v_pk_mul_f32 v[36:37], v[68:69], v[36:37] op_sel_hi:[0,1]
	v_pk_mul_f32 v[34:35], v[68:69], v[34:35] op_sel_hi:[0,1]
	v_pk_mul_f32 v[32:33], v[68:69], v[32:33] op_sel_hi:[0,1]
	v_pk_mul_f32 v[30:31], v[68:69], v[30:31] op_sel_hi:[0,1]
	v_pk_mul_f32 v[28:29], v[68:69], v[28:29] op_sel_hi:[0,1]
	v_pk_mul_f32 v[26:27], v[68:69], v[26:27] op_sel_hi:[0,1]
	v_pk_mul_f32 v[24:25], v[68:69], v[24:25] op_sel_hi:[0,1]
	v_pk_mul_f32 v[22:23], v[68:69], v[22:23] op_sel_hi:[0,1]
	v_pk_mul_f32 v[20:21], v[68:69], v[20:21] op_sel_hi:[0,1]
	v_pk_mul_f32 v[18:19], v[68:69], v[18:19] op_sel_hi:[0,1]
	v_pk_mul_f32 v[16:17], v[68:69], v[16:17] op_sel_hi:[0,1]

.LBB0_840:
	s_add_i32 s0, s78, 0xffff8000
	s_and_b32 s10, s0, 0x18000
	v_add_u32_e32 v76, s10, v237
	v_add_u32_e32 v76, v76, v228
	ds_read_b128 v[80:83], v76 offset:16384
	ds_read_b128 v[84:87], v76 offset:20480
	ds_read_b128 v[88:91], v76 offset:24576
	ds_read_b128 v[92:95], v76 offset:28672
	v_max3_f32 v68, v96, v97, v98
	v_max3_f32 v70, v104, v105, v106
	v_max3_f32 v71, v112, v113, v114
	v_max3_f32 v72, v120, v121, v122
	v_max3_f32 v68, v68, v99, v100
	v_max3_f32 v70, v70, v107, v108
	v_max3_f32 v71, v71, v115, v116
	v_max3_f32 v72, v72, v123, v124
	s_waitcnt lgkmcnt(3)
	v_mfma_f32_32x32x16_bf16 v[0:15], v[80:83], v[64:67], v[0:15]
	v_max3_f32 v68, v68, v101, v102
	v_max3_f32 v70, v70, v109, v110
	v_max3_f32 v71, v71, v117, v118
	v_max3_f32 v72, v72, v125, v126
	s_xor_b32 s33, s10, 0x10000
	v_max3_f32 v68, v68, v103, v70
	v_max3_f32 v70, v71, v119, v72
	s_waitcnt lgkmcnt(2)
	v_mfma_f32_32x32x16_bf16 v[48:63], v[84:87], v[64:67], v[48:63]
	v_max3_f32 v68, v68, v111, v127
	v_max3_f32 v68, v68, v70, v70
	v_mov_b32_e32 v70, v68
	s_nop 1
	v_permlane32_swap_b32_e32 v68, v70
	v_max3_f32 v68, v68, v70, v70
	v_max_f32_e32 v141, v212, v68
	s_waitcnt lgkmcnt(1)
	v_mfma_f32_32x32x16_bf16 v[32:47], v[88:91], v[64:67], v[32:47]
	v_sub_f32_e32 v70, v212, v141
	v_exp_f32_e32 v140, v70
	v_add_f32_e32 v70, 0x41000000, v212
	v_cmp_gt_f32_e32 vcc, v68, v70
	s_cmp_eq_u64 vcc, 0
	v_mul_f32_e32 v68, v69, v140
	s_cselect_b64 s[0:1], -1, 0
	v_cndmask_b32_e64 v194, v68, v69, s[0:1]
	s_waitcnt lgkmcnt(0)
	v_mfma_f32_32x32x16_bf16 v[16:31], v[92:95], v[64:67], v[16:31]
	v_add_u32_e32 v182, s10, v237
	v_add_u32_e32 v158, s33, v235
	v_add_u32_e32 v88, v158, v231
	v_add_u32_e32 v150, v182, v231
	v_add_u32_e32 v159, v158, v230
	v_cndmask_b32_e64 v212, v141, v212, s[0:1]
	v_add_u32_e32 v141, v182, v230
	v_sub_f32_e32 v180, v102, v212
	v_sub_f32_e32 v181, v103, v212
	v_sub_f32_e32 v116, v116, v212
	v_sub_f32_e32 v117, v117, v212
	v_sub_f32_e32 v108, v108, v212
	v_sub_f32_e32 v109, v109, v212
	v_sub_f32_e32 v124, v124, v212
	v_sub_f32_e32 v125, v125, v212
	v_exp_f32_e32 v116, v116
	v_exp_f32_e32 v117, v117
	v_exp_f32_e32 v108, v108
	v_exp_f32_e32 v124, v124
	v_exp_f32_e32 v109, v109
	v_add_u32_e32 v68, v158, v228
	v_add_u32_e32 v158, v158, v229
	v_exp_f32_e32 v125, v125
	v_sub_f32_e32 v114, v114, v212
	v_sub_f32_e32 v115, v115, v212
	v_sub_f32_e32 v118, v118, v212
	v_sub_f32_e32 v119, v119, v212
	v_sub_f32_e32 v122, v122, v212
	v_sub_f32_e32 v123, v123, v212
	v_sub_f32_e32 v110, v110, v212
	v_sub_f32_e32 v111, v111, v212
	ds_read_b128 v[64:67], v68
	ds_read_b128 v[80:83], v68 offset:4096
	ds_read_b128 v[84:87], v88
	ds_read_b128 v[142:145], v88 offset:4096
	v_sub_f32_e32 v126, v126, v212
	v_sub_f32_e32 v127, v127, v212
	v_sub_f32_e32 v106, v106, v212
	v_sub_f32_e32 v107, v107, v212
	v_exp_f32_e32 v114, v114
	v_exp_f32_e32 v115, v115
	v_exp_f32_e32 v118, v118
	s_waitcnt lgkmcnt(0)
	v_mfma_f32_32x32x16_bf16 v[64:79], v[64:67], v[160:163], 0
	v_exp_f32_e32 v119, v119
	v_exp_f32_e32 v122, v122
	v_exp_f32_e32 v123, v123
	v_exp_f32_e32 v110, v110
	v_exp_f32_e32 v126, v126
	v_exp_f32_e32 v111, v111
	v_exp_f32_e32 v127, v127
	v_mfma_f32_32x32x16_bf16 v[64:79], v[84:87], v[164:167], v[64:79]
	v_sub_f32_e32 v104, v104, v212
	v_sub_f32_e32 v105, v105, v212
	v_sub_f32_e32 v112, v112, v212
	v_sub_f32_e32 v113, v113, v212
	v_sub_f32_e32 v120, v120, v212
	v_sub_f32_e32 v121, v121, v212
	v_cvt_pk_bf16_f32 v183, v118, v119
	v_exp_f32_e32 v112, v112
	v_exp_f32_e32 v113, v113
	v_exp_f32_e32 v120, v120
	v_mfma_f32_32x32x16_bf16 v[80:95], v[80:83], v[160:163], 0
	v_exp_f32_e32 v121, v121
	v_cvt_pk_bf16_f32 v186, v108, v109
	v_cvt_pk_bf16_f32 v187, v110, v111
	v_mfma_f32_32x32x16_bf16 v[80:95], v[142:145], v[164:167], v[80:95]
	ds_read_b128 v[142:145], v150 offset:16384
	ds_read_b128 v[146:149], v150 offset:20480
	s_waitcnt lgkmcnt(0)
	v_mfma_f32_32x32x16_bf16 v[0:15], v[142:145], v[136:139], v[0:15]
	ds_read_b128 v[142:145], v150 offset:24576
	ds_read_b128 v[150:153], v150 offset:28672
	ds_read_b128 v[154:157], v159
	ds_read_b128 v[176:179], v159 offset:4096
	v_mfma_f32_32x32x16_bf16 v[48:63], v[146:149], v[136:139], v[48:63]
	ds_read_b128 v[146:149], v158
	ds_read_b128 v[238:241], v158 offset:4096
	v_sub_f32_e32 v158, v96, v212
	v_sub_f32_e32 v159, v97, v212
	s_waitcnt lgkmcnt(0)
	v_mfma_f32_32x32x16_bf16 v[32:47], v[142:145], v[136:139], v[32:47]
	v_sub_f32_e32 v142, v98, v212
	v_sub_f32_e32 v143, v99, v212
	v_sub_f32_e32 v144, v100, v212
	v_sub_f32_e32 v145, v101, v212
	ds_read_b128 v[96:99], v141 offset:16384
	ds_read_b128 v[100:103], v141 offset:20480
	s_waitcnt lgkmcnt(0)
	v_mfma_f32_32x32x16_bf16 v[0:15], v[96:99], v[132:135], v[0:15]
	ds_read_b128 v[96:99], v141 offset:24576
	v_mfma_f32_32x32x16_bf16 v[48:63], v[100:103], v[132:135], v[48:63]
	ds_read_b128 v[100:103], v141 offset:28672
	v_add_u32_e32 v141, v182, v229
	v_cvt_pk_bf16_f32 v182, v116, v117
	v_mfma_f32_32x32x16_bf16 v[16:31], v[150:153], v[136:139], v[16:31]
	v_exp_f32_e32 v138, v142
	v_exp_f32_e32 v139, v143
	v_exp_f32_e32 v142, v144
	v_exp_f32_e32 v143, v145
	v_exp_f32_e32 v144, v180
	v_exp_f32_e32 v145, v181
	v_exp_f32_e32 v136, v158
	s_waitcnt lgkmcnt(0)
	v_mfma_f32_32x32x16_bf16 v[32:47], v[96:99], v[132:135], v[32:47]
	ds_read_b128 v[96:99], v141 offset:16384
	v_exp_f32_e32 v137, v159
	v_cvt_pk_bf16_f32 v180, v112, v113
	v_cvt_pk_bf16_f32 v181, v114, v115
	v_add_f32_e32 v152, v136, v112
	v_add_f32_e32 v153, v137, v113
	v_mfma_f32_32x32x16_bf16 v[16:31], v[100:103], v[132:135], v[16:31]
	v_add_f32_e64 v100, v108, v124
	v_add_f32_e64 v101, v109, v125
	v_add_f32_e64 v102, v142, v116
	v_add_f32_e64 v103, v143, v117
	v_exp_f32_e32 v134, v106
	v_exp_f32_e32 v135, v107
	v_exp_f32_e32 v132, v104
	v_exp_f32_e32 v133, v105
	v_add_f32_e32 v106, v138, v114
	v_add_f32_e32 v107, v139, v115
	v_mfma_f32_32x32x16_bf16 v[64:79], v[154:157], v[168:171], v[64:79]
	v_add_f32_e64 v154, v102, v100
	v_add_f32_e64 v155, v103, v101
	ds_read_b128 v[100:103], v141 offset:20480
	v_add_f32_e64 v104, v134, v122
	v_add_f32_e64 v105, v135, v123
	v_add_f32_e32 v150, v132, v120
	v_add_f32_e32 v151, v133, v121
	v_add_f32_e32 v104, v106, v104
	v_add_f32_e32 v105, v107, v105
	v_cvt_pk_bf16_f32 v184, v132, v133
	v_cvt_pk_bf16_f32 v185, v134, v135
	v_mfma_f32_32x32x16_bf16 v[64:79], v[146:149], v[172:175], v[64:79]
	v_add_f32_e64 v146, v110, v126
	v_add_f32_e64 v147, v111, v127
	v_add_f32_e64 v148, v144, v118
	v_add_f32_e64 v149, v145, v119
	s_waitcnt lgkmcnt(0)
	v_mfma_f32_32x32x16_bf16 v[0:15], v[96:99], v[128:131], v[0:15]
	v_add_f32_e64 v98, v148, v146
	v_add_f32_e64 v99, v149, v147
	v_add_f32_e64 v96, v152, v150
	v_add_f32_e64 v97, v153, v151
	v_add_f32_e64 v98, v104, v98
	v_add_f32_e64 v99, v105, v99
	ds_read_b128 v[104:107], v141 offset:24576
	v_add_f32_e32 v96, v96, v154
	v_add_f32_e32 v97, v97, v155
	s_nop 0
	v_add_f32_e32 v96, v96, v97
	v_mfma_f32_32x32x16_bf16 v[48:63], v[100:103], v[128:131], v[48:63]
	ds_read_b128 v[100:103], v141 offset:28672
	v_add_f32_e32 v97, v98, v99
	v_add_f32_e32 v146, v96, v97
	v_cvt_pk_bf16_f32 v96, v136, v137
	v_cvt_pk_bf16_f32 v97, v138, v139
	v_cvt_pk_bf16_f32 v98, v142, v143
	v_cvt_pk_bf16_f32 v99, v144, v145
	v_mfma_f32_32x32x16_bf16 v[80:95], v[176:179], v[168:171], v[80:95]
	v_cvt_pk_bf16_f32 v176, v120, v121
	v_cvt_pk_bf16_f32 v177, v122, v123
	v_cvt_pk_bf16_f32 v178, v124, v125
	v_cvt_pk_bf16_f32 v179, v126, v127
	s_waitcnt lgkmcnt(0)
	v_mfma_f32_32x32x16_bf16 v[32:47], v[104:107], v[128:131], v[32:47]
	v_mfma_f32_32x32x16_bf16 v[16:31], v[100:103], v[128:131], v[16:31]
	v_add_f32_e32 v100, v194, v146
	v_mfma_f32_32x32x16_bf16 v[80:95], v[238:241], v[172:175], v[80:95]
	s_cbranch_vccz .LBB0_842
	v_pk_mul_f32 v[14:15], v[140:141], v[14:15] op_sel_hi:[0,1]
	v_pk_mul_f32 v[12:13], v[140:141], v[12:13] op_sel_hi:[0,1]
	v_pk_mul_f32 v[10:11], v[140:141], v[10:11] op_sel_hi:[0,1]
	v_pk_mul_f32 v[8:9], v[140:141], v[8:9] op_sel_hi:[0,1]
	v_pk_mul_f32 v[6:7], v[140:141], v[6:7] op_sel_hi:[0,1]
	v_pk_mul_f32 v[4:5], v[140:141], v[4:5] op_sel_hi:[0,1]
	v_pk_mul_f32 v[2:3], v[140:141], v[2:3] op_sel_hi:[0,1]
	v_pk_mul_f32 v[0:1], v[140:141], v[0:1] op_sel_hi:[0,1]
	v_pk_mul_f32 v[62:63], v[140:141], v[62:63] op_sel_hi:[0,1]
	v_pk_mul_f32 v[60:61], v[140:141], v[60:61] op_sel_hi:[0,1]
	v_pk_mul_f32 v[58:59], v[140:141], v[58:59] op_sel_hi:[0,1]
	v_pk_mul_f32 v[56:57], v[140:141], v[56:57] op_sel_hi:[0,1]
	v_pk_mul_f32 v[54:55], v[140:141], v[54:55] op_sel_hi:[0,1]
	v_pk_mul_f32 v[52:53], v[140:141], v[52:53] op_sel_hi:[0,1]
	v_pk_mul_f32 v[50:51], v[140:141], v[50:51] op_sel_hi:[0,1]
	v_pk_mul_f32 v[48:49], v[140:141], v[48:49] op_sel_hi:[0,1]
	v_pk_mul_f32 v[46:47], v[140:141], v[46:47] op_sel_hi:[0,1]
	v_pk_mul_f32 v[44:45], v[140:141], v[44:45] op_sel_hi:[0,1]
	v_pk_mul_f32 v[42:43], v[140:141], v[42:43] op_sel_hi:[0,1]
	v_pk_mul_f32 v[40:41], v[140:141], v[40:41] op_sel_hi:[0,1]
	v_pk_mul_f32 v[38:39], v[140:141], v[38:39] op_sel_hi:[0,1]
	v_pk_mul_f32 v[36:37], v[140:141], v[36:37] op_sel_hi:[0,1]
	v_pk_mul_f32 v[34:35], v[140:141], v[34:35] op_sel_hi:[0,1]
	v_pk_mul_f32 v[32:33], v[140:141], v[32:33] op_sel_hi:[0,1]
	v_pk_mul_f32 v[30:31], v[140:141], v[30:31] op_sel_hi:[0,1]
	v_pk_mul_f32 v[28:29], v[140:141], v[28:29] op_sel_hi:[0,1]
	v_pk_mul_f32 v[26:27], v[140:141], v[26:27] op_sel_hi:[0,1]
	v_pk_mul_f32 v[24:25], v[140:141], v[24:25] op_sel_hi:[0,1]
	v_pk_mul_f32 v[22:23], v[140:141], v[22:23] op_sel_hi:[0,1]
	v_pk_mul_f32 v[20:21], v[140:141], v[20:21] op_sel_hi:[0,1]
	v_pk_mul_f32 v[18:19], v[140:141], v[18:19] op_sel_hi:[0,1]
	v_pk_mul_f32 v[16:17], v[140:141], v[16:17] op_sel_hi:[0,1]

.Lattn2_nomask:
	s_add_i32 s9, s34, 0x10000
	s_and_b32 s33, s9, 0x18000
	s_and_b32 s10, s34, 0x18000
	v_add_u32_e32 v239, s33, v237
	v_add_u32_e32 v250, v239, v230
	ds_read_b128 v[128:131], v250 offset:16384
	ds_read_b128 v[132:135], v250 offset:20480
	ds_read_b128 v[136:139], v250 offset:24576
	ds_read_b128 v[140:143], v250 offset:28672
	v_add_u32_e32 v251, s10, v236
	v_add_u32_e32 v250, v251, v230
	ds_read_b128 v[144:147], v250
	ds_read_b128 v[148:151], v250 offset:4096
	v_add_u32_e32 v250, v251, v233
	ds_read_b128 v[152:155], v250
	ds_read_b128 v[156:159], v250 offset:4096
	s_add_i32 s0, s74, s64
	s_addk_i32 s0, 0xc0
	s_mul_i32 s0, s0, s14
	s_add_i32 s0, s0, s92
	s_addk_i32 s0, 0x1c00
	s_add_u32 s98, s82, s0
	s_addc_u32 s99, s83, 0
	s_lshl_b32 s1, s17, 13
	s_add_u32 s46, s76, s1
	s_addc_u32 s47, s77, 0
	s_add_i32 s0, s34, 0x8000
	s_and_b32 s0, s0, 0x18000
	s_add_i32 s0, s5, s0
	s_mov_b32 m0, s0
	s_nop 0
	global_load_lds_dwordx4 v244, s[98:99]
	s_add_i32 m0, s0, 0x2000
	s_add_u32 s98, s98, 0x80
	s_addc_u32 s99, s99, 0
	global_load_lds_dwordx4 v244, s[98:99]
	s_add_i32 m0, s0, 0x4000
	s_nop 0
	global_load_lds_dwordx4 v245, s[46:47]
	s_add_i32 m0, s0, 0x6000
	s_add_u32 s46, s46, 0x80000
	s_addc_u32 s47, s47, 0
	global_load_lds_dwordx4 v245, s[46:47]
	v_max3_f32 v246, v64, v65, v66
	v_max3_f32 v247, v72, v73, v74
	v_max3_f32 v248, v80, v81, v82
	v_max3_f32 v249, v88, v89, v90
	v_max3_f32 v246, v246, v67, v68
	v_max3_f32 v247, v247, v75, v76
	v_max3_f32 v248, v248, v83, v84
	v_max3_f32 v249, v249, v91, v92
	s_waitcnt lgkmcnt(7)
	v_mfma_f32_32x32x16_bf16 v[0:15], v[128:131], v[96:99], v[0:15]
	v_max3_f32 v246, v246, v69, v70
	v_max3_f32 v247, v247, v77, v78
	v_max3_f32 v248, v248, v85, v86
	v_max3_f32 v249, v249, v93, v94
	v_max3_f32 v246, v246, v71, v247
	v_max3_f32 v247, v248, v87, v249
	s_waitcnt lgkmcnt(6)
	v_mfma_f32_32x32x16_bf16 v[48:63], v[132:135], v[96:99], v[48:63]
	v_max3_f32 v246, v246, v79, v95
	v_max3_f32 v246, v246, v247, v247
	v_mov_b32_e32 v247, v246
	s_nop 1
	v_permlane32_swap_b32_e32 v246, v247
	v_max3_f32 v246, v246, v247, v247
	v_max_f32_e32 v251, v214, v246
	s_waitcnt lgkmcnt(5)
	v_mfma_f32_32x32x16_bf16 v[32:47], v[136:139], v[96:99], v[32:47]
	v_sub_f32_e32 v247, v214, v251
	v_exp_f32_e32 v250, v247
	v_add_f32_e32 v247, 0x41000000, v214
	v_cmp_gt_f32_e32 vcc, v246, v247
	s_cmp_eq_u64 vcc, 0
	v_mul_f32_e32 v246, v100, v250
	s_cselect_b64 s[0:1], -1, 0
	v_cndmask_b32_e64 v194, v246, v100, s[0:1]
	s_waitcnt lgkmcnt(4)
	v_mfma_f32_32x32x16_bf16 v[16:31], v[140:143], v[96:99], v[16:31]
	v_cndmask_b32_e64 v214, v251, v214, s[0:1]
	v_sub_f32_e32 v140, v92, v214
	v_sub_f32_e32 v141, v93, v214
	v_sub_f32_e32 v138, v90, v214
	v_sub_f32_e32 v139, v91, v214
	s_waitcnt lgkmcnt(3)
	v_mfma_f32_32x32x16_bf16 v[96:111], v[144:147], v[160:163], 0
	v_sub_f32_e32 v142, v94, v214
	v_sub_f32_e32 v143, v95, v214
	v_sub_f32_e32 v92, v80, v214
	v_sub_f32_e32 v93, v81, v214
	v_sub_f32_e32 v128, v82, v214
	v_sub_f32_e32 v129, v83, v214
	s_waitcnt lgkmcnt(2)
	v_mfma_f32_32x32x16_bf16 v[112:127], v[148:151], v[160:163], 0
	v_sub_f32_e32 v130, v68, v214
	v_sub_f32_e32 v131, v69, v214
	v_sub_f32_e32 v90, v64, v214
	v_sub_f32_e32 v91, v65, v214
	v_sub_f32_e32 v132, v84, v214
	v_sub_f32_e32 v133, v85, v214
	s_waitcnt lgkmcnt(1)
	v_mfma_f32_32x32x16_bf16 v[96:111], v[152:155], v[164:167], v[96:111]
	v_sub_f32_e32 v94, v66, v214
	v_sub_f32_e32 v95, v67, v214
	v_sub_f32_e32 v134, v86, v214
	v_sub_f32_e32 v135, v87, v214
	v_sub_f32_e32 v136, v88, v214
	v_sub_f32_e32 v137, v89, v214
	s_waitcnt lgkmcnt(0)
	v_mfma_f32_32x32x16_bf16 v[112:127], v[156:159], v[164:167], v[112:127]
	v_sub_f32_e32 v144, v70, v214
	v_sub_f32_e32 v145, v71, v214
	v_sub_f32_e32 v148, v74, v214
	v_sub_f32_e32 v149, v75, v214
	v_sub_f32_e32 v150, v76, v214
	v_sub_f32_e32 v151, v77, v214
	v_sub_f32_e32 v146, v72, v214
	v_sub_f32_e32 v147, v73, v214
	v_sub_f32_e32 v152, v78, v214
	v_sub_f32_e32 v153, v79, v214
	v_mov_b32_e32 v68, v250
	s_branch .Lattn_body_2
.LBB0_864:
	v_max3_f32 v64, v144, v145, v146
	v_max3_f32 v65, v152, v153, v154
	v_max3_f32 v66, v128, v129, v130
	v_max3_f32 v67, v136, v137, v138
	s_add_i32 s9, s34, 0x10000
	v_max3_f32 v64, v64, v147, v148
	v_max3_f32 v65, v65, v155, v156
	v_max3_f32 v66, v66, v131, v132
	v_max3_f32 v67, v67, v139, v140
	s_and_b32 s33, s9, 0x18000
	v_max3_f32 v64, v64, v149, v150
	v_max3_f32 v65, v65, v157, v158
	v_max3_f32 v66, v66, v133, v134
	v_max3_f32 v67, v67, v141, v142
	s_and_b32 s10, s34, 0x18000
	v_max3_f32 v64, v64, v151, v65
	v_max3_f32 v65, v66, v135, v67
	v_max_f32_e32 v66, v214, v214
	v_max3_f32 v64, v64, v159, v143
	s_nop 0
	v_max3_f32 v64, v64, v65, v65
	s_nop 0
	v_mov_b32_e32 v65, v64
	s_nop 1
	v_permlane32_swap_b32_e32 v64, v65
	v_max3_f32 v64, v64, v65, v65
	s_nop 0
	v_max_f32_e32 v65, v64, v64
	v_max_f32_e32 v69, v66, v65
	v_sub_f32_e32 v65, v214, v69
	v_exp_f32_e32 v68, v65
	v_add_f32_e32 v65, 0x41000000, v214
	v_cmp_gt_f32_e32 vcc, v64, v65
	s_cmp_eq_u64 vcc, 0
	v_mul_f32_e32 v64, v100, v68
	s_cselect_b64 s[0:1], -1, 0
	v_cndmask_b32_e64 v194, v64, v100, s[0:1]
	v_cndmask_b32_e64 v214, v69, v214, s[0:1]
	v_mov_b32_e32 v215, v214
	v_sub_f32_e32 v92, v128, v214
	v_sub_f32_e32 v93, v129, v215
	v_sub_f32_e32 v128, v130, v214
	v_sub_f32_e32 v129, v131, v215
	v_sub_f32_e32 v130, v148, v214
	v_sub_f32_e32 v131, v149, v215
	v_sub_f32_e32 v90, v144, v214
	v_sub_f32_e32 v91, v145, v215
	v_sub_f32_e32 v132, v132, v214
	v_sub_f32_e32 v133, v133, v215
	v_sub_f32_e32 v144, v150, v214
	v_sub_f32_e32 v145, v151, v215
	v_sub_f32_e32 v148, v154, v214
	v_sub_f32_e32 v149, v155, v215
	v_sub_f32_e32 v150, v156, v214
	v_sub_f32_e32 v151, v157, v215
	v_sub_f32_e32 v140, v140, v214
	v_sub_f32_e32 v141, v141, v215
	v_sub_f32_e32 v138, v138, v214
	v_sub_f32_e32 v139, v139, v215
	v_sub_f32_e32 v94, v146, v214
	v_sub_f32_e32 v95, v147, v215
	v_sub_f32_e32 v146, v152, v214
	v_sub_f32_e32 v147, v153, v215
	v_sub_f32_e32 v152, v158, v214
	v_sub_f32_e32 v153, v159, v215
	v_sub_f32_e32 v142, v142, v214
	v_sub_f32_e32 v143, v143, v215
	v_sub_f32_e32 v134, v134, v214
	v_sub_f32_e32 v135, v135, v215
	v_sub_f32_e32 v136, v136, v214
	v_sub_f32_e32 v137, v137, v215
	v_add_u32_e32 v74, s33, v237
	v_add_u32_e32 v74, v74, v230
	ds_read_b128 v[64:67], v74 offset:16384
	ds_read_b128 v[70:73], v74 offset:20480
	s_waitcnt lgkmcnt(0)
	v_mfma_f32_32x32x16_bf16 v[0:15], v[64:67], v[96:99], v[0:15]
	v_mfma_f32_32x32x16_bf16 v[48:63], v[70:73], v[96:99], v[48:63]
	ds_read_b128 v[64:67], v74 offset:24576
	ds_read_b128 v[70:73], v74 offset:28672
	s_waitcnt lgkmcnt(0)
	v_mfma_f32_32x32x16_bf16 v[32:47], v[64:67], v[96:99], v[32:47]
	v_mfma_f32_32x32x16_bf16 v[16:31], v[70:73], v[96:99], v[16:31]
	v_add_u32_e32 v74, s10, v236
	v_add_u32_e32 v74, v74, v230
	ds_read_b128 v[64:67], v74
	ds_read_b128 v[70:73], v74 offset:4096
	v_add_u32_e32 v74, s10, v236
	v_add_u32_e32 v74, v74, v233
	s_waitcnt lgkmcnt(0)
	v_mfma_f32_32x32x16_bf16 v[96:111], v[64:67], v[160:163], 0
	ds_read_b128 v[64:67], v74
	ds_read_b128 v[74:77], v74 offset:4096
	v_mfma_f32_32x32x16_bf16 v[112:127], v[70:73], v[160:163], 0
	s_waitcnt lgkmcnt(0)
	v_mfma_f32_32x32x16_bf16 v[96:111], v[64:67], v[164:167], v[96:111]
	v_mfma_f32_32x32x16_bf16 v[112:127], v[74:77], v[164:167], v[112:127]
	v_add_u32_e32 v239, s33, v237
.Lattn_body_2:
	v_add_u32_e32 v86, s10, v236
	v_add_u32_e32 v78, v239, v233
	v_add_u32_e32 v82, v86, v232
	v_add_u32_e32 v69, v239, v232
	v_exp_f32_e32 v130, v130
	v_exp_f32_e32 v154, v132
	v_exp_f32_e32 v131, v131
	v_exp_f32_e32 v155, v133
	v_add_u32_e32 v86, v86, v231
	v_exp_f32_e32 v158, v138
	v_exp_f32_e32 v159, v139
	v_exp_f32_e32 v94, v94
	v_exp_f32_e32 v128, v128
	v_exp_f32_e32 v95, v95
	v_exp_f32_e32 v129, v129
	v_exp_f32_e32 v132, v144
	v_exp_f32_e32 v144, v134
	v_exp_f32_e32 v133, v145
	v_exp_f32_e32 v145, v135
	v_exp_f32_e32 v148, v148
	v_exp_f32_e32 v149, v149
	v_exp_f32_e32 v142, v142
	v_exp_f32_e32 v143, v143
	ds_read_b128 v[64:67], v78 offset:16384
	ds_read_b128 v[70:73], v78 offset:20480
	v_exp_f32_e32 v90, v90
	v_exp_f32_e32 v92, v92
	v_exp_f32_e32 v91, v91
	v_exp_f32_e32 v93, v93
	v_exp_f32_e32 v146, v146
	v_exp_f32_e32 v156, v136
	v_exp_f32_e32 v147, v147
	v_exp_f32_e32 v157, v137
	v_add_f32_e32 v136, v90, v92
	v_add_f32_e32 v137, v91, v93
	s_waitcnt lgkmcnt(0)
	v_mfma_f32_32x32x16_bf16 v[0:15], v[64:67], v[184:187], v[0:15]
	ds_read_b128 v[64:67], v78 offset:24576
	ds_read_b128 v[74:77], v78 offset:28672
	ds_read_b128 v[78:81], v82
	ds_read_b128 v[82:85], v82 offset:4096
	v_mfma_f32_32x32x16_bf16 v[48:63], v[70:73], v[184:187], v[48:63]
	ds_read_b128 v[70:73], v86
	ds_read_b128 v[86:89], v86 offset:4096
	s_waitcnt lgkmcnt(0)
	v_mfma_f32_32x32x16_bf16 v[32:47], v[64:67], v[184:187], v[32:47]
	ds_read_b128 v[64:67], v69 offset:16384
	v_mfma_f32_32x32x16_bf16 v[16:31], v[74:77], v[184:187], v[16:31]
	ds_read_b128 v[74:77], v69 offset:20480
	s_waitcnt lgkmcnt(0)
	v_mfma_f32_32x32x16_bf16 v[0:15], v[64:67], v[180:183], v[0:15]
	ds_read_b128 v[64:67], v69 offset:24576
	v_mfma_f32_32x32x16_bf16 v[96:111], v[78:81], v[168:171], v[96:111]
	v_exp_f32_e32 v78, v150
	v_exp_f32_e32 v80, v140
	v_exp_f32_e32 v79, v151
	v_exp_f32_e32 v81, v141
	v_exp_f32_e32 v150, v152
	v_exp_f32_e32 v151, v153
	v_mfma_f32_32x32x16_bf16 v[48:63], v[74:77], v[180:183], v[48:63]
	ds_read_b128 v[74:77], v69 offset:28672
	v_add_u32_e32 v69, v239, v231
	v_add_f32_e64 v134, v150, v142
	v_add_f32_e64 v135, v151, v143
	s_waitcnt lgkmcnt(0)
	v_mfma_f32_32x32x16_bf16 v[32:47], v[64:67], v[180:183], v[32:47]
	ds_read_b128 v[64:67], v69 offset:16384
	v_mfma_f32_32x32x16_bf16 v[96:111], v[70:73], v[172:175], v[96:111]
	v_add_f32_e64 v70, v78, v80
	v_add_f32_e64 v71, v79, v81
	v_add_f32_e64 v72, v130, v154
	v_add_f32_e64 v73, v131, v155
	v_add_f32_e64 v138, v72, v70
	v_add_f32_e64 v139, v73, v71
	ds_read_b128 v[70:73], v69 offset:20480
	v_mfma_f32_32x32x16_bf16 v[16:31], v[74:77], v[180:183], v[16:31]
	v_add_f32_e64 v74, v148, v158
	v_add_f32_e64 v75, v149, v159
	v_add_f32_e64 v76, v94, v128
	v_add_f32_e64 v77, v95, v129
	v_add_f32_e64 v74, v76, v74
	v_add_f32_e64 v75, v77, v75
	v_mfma_f32_32x32x16_bf16 v[112:127], v[82:85], v[168:171], v[112:127]
	v_add_f32_e64 v82, v132, v144
	v_add_f32_e64 v83, v133, v145
	v_add_f32_e64 v84, v146, v156
	v_add_f32_e64 v85, v147, v157
	s_waitcnt lgkmcnt(0)
	v_mfma_f32_32x32x16_bf16 v[0:15], v[64:67], v[176:179], v[0:15]
	v_add_f32_e64 v66, v82, v134
	v_add_f32_e64 v67, v83, v135
	v_add_f32_e64 v64, v136, v84
	v_add_f32_e64 v65, v137, v85
	v_add_f32_e64 v66, v74, v66
	v_add_f32_e64 v67, v75, v67
	ds_read_b128 v[74:77], v69 offset:24576
	v_add_f32_e32 v64, v64, v138
	v_add_f32_e32 v65, v65, v139
	v_cvt_pk_bf16_f32 v134, v154, v155
	v_add_f32_e32 v64, v64, v65
	v_mfma_f32_32x32x16_bf16 v[48:63], v[70:73], v[176:179], v[48:63]
	ds_read_b128 v[70:73], v69 offset:28672
	v_add_f32_e32 v65, v66, v67
	v_add_f32_e32 v82, v64, v65
	v_cvt_pk_bf16_f32 v64, v90, v91
	v_cvt_pk_bf16_f32 v65, v94, v95
	v_cvt_pk_bf16_f32 v66, v130, v131
	v_cvt_pk_bf16_f32 v67, v132, v133
	s_waitcnt lgkmcnt(0)
	v_mfma_f32_32x32x16_bf16 v[32:47], v[74:77], v[176:179], v[32:47]
	v_cvt_pk_bf16_f32 v132, v92, v93
	v_cvt_pk_bf16_f32 v133, v128, v129
	v_cvt_pk_bf16_f32 v135, v144, v145
	v_cvt_pk_bf16_f32 v136, v146, v147
	v_cvt_pk_bf16_f32 v137, v148, v149
	v_cvt_pk_bf16_f32 v138, v78, v79
	v_cvt_pk_bf16_f32 v139, v150, v151
	v_mfma_f32_32x32x16_bf16 v[16:31], v[70:73], v[176:179], v[16:31]
	v_cvt_pk_bf16_f32 v128, v156, v157
	v_cvt_pk_bf16_f32 v129, v158, v159
	v_cvt_pk_bf16_f32 v130, v80, v81
	v_cvt_pk_bf16_f32 v131, v142, v143
	v_add_f32_e32 v69, v194, v82
	v_mfma_f32_32x32x16_bf16 v[112:127], v[86:89], v[172:175], v[112:127]
	s_cbranch_vccz .LBB0_866
	v_pk_mul_f32 v[14:15], v[68:69], v[14:15] op_sel_hi:[0,1]
	v_pk_mul_f32 v[12:13], v[68:69], v[12:13] op_sel_hi:[0,1]
	v_pk_mul_f32 v[10:11], v[68:69], v[10:11] op_sel_hi:[0,1]
	v_pk_mul_f32 v[8:9], v[68:69], v[8:9] op_sel_hi:[0,1]
	v_pk_mul_f32 v[6:7], v[68:69], v[6:7] op_sel_hi:[0,1]
	v_pk_mul_f32 v[4:5], v[68:69], v[4:5] op_sel_hi:[0,1]
	v_pk_mul_f32 v[2:3], v[68:69], v[2:3] op_sel_hi:[0,1]
	v_pk_mul_f32 v[0:1], v[68:69], v[0:1] op_sel_hi:[0,1]
	v_pk_mul_f32 v[62:63], v[68:69], v[62:63] op_sel_hi:[0,1]
	v_pk_mul_f32 v[60:61], v[68:69], v[60:61] op_sel_hi:[0,1]
	v_pk_mul_f32 v[58:59], v[68:69], v[58:59] op_sel_hi:[0,1]
	v_pk_mul_f32 v[56:57], v[68:69], v[56:57] op_sel_hi:[0,1]
	v_pk_mul_f32 v[54:55], v[68:69], v[54:55] op_sel_hi:[0,1]
	v_pk_mul_f32 v[52:53], v[68:69], v[52:53] op_sel_hi:[0,1]
	v_pk_mul_f32 v[50:51], v[68:69], v[50:51] op_sel_hi:[0,1]
	v_pk_mul_f32 v[48:49], v[68:69], v[48:49] op_sel_hi:[0,1]
	v_pk_mul_f32 v[46:47], v[68:69], v[46:47] op_sel_hi:[0,1]
	v_pk_mul_f32 v[44:45], v[68:69], v[44:45] op_sel_hi:[0,1]
	v_pk_mul_f32 v[42:43], v[68:69], v[42:43] op_sel_hi:[0,1]
	v_pk_mul_f32 v[40:41], v[68:69], v[40:41] op_sel_hi:[0,1]
	v_pk_mul_f32 v[38:39], v[68:69], v[38:39] op_sel_hi:[0,1]
	v_pk_mul_f32 v[36:37], v[68:69], v[36:37] op_sel_hi:[0,1]
	v_pk_mul_f32 v[34:35], v[68:69], v[34:35] op_sel_hi:[0,1]
	v_pk_mul_f32 v[32:33], v[68:69], v[32:33] op_sel_hi:[0,1]
	v_pk_mul_f32 v[30:31], v[68:69], v[30:31] op_sel_hi:[0,1]
	v_pk_mul_f32 v[28:29], v[68:69], v[28:29] op_sel_hi:[0,1]
	v_pk_mul_f32 v[26:27], v[68:69], v[26:27] op_sel_hi:[0,1]
	v_pk_mul_f32 v[24:25], v[68:69], v[24:25] op_sel_hi:[0,1]
	v_pk_mul_f32 v[22:23], v[68:69], v[22:23] op_sel_hi:[0,1]
	v_pk_mul_f32 v[20:21], v[68:69], v[20:21] op_sel_hi:[0,1]
	v_pk_mul_f32 v[18:19], v[68:69], v[18:19] op_sel_hi:[0,1]
	v_pk_mul_f32 v[16:17], v[68:69], v[16:17] op_sel_hi:[0,1]

.LBB0_870:
	s_add_i32 s0, s34, 0xffff8000
	s_and_b32 s33, s0, 0x18000
	v_add_u32_e32 v76, s33, v237
	v_add_u32_e32 v76, v76, v230
	ds_read_b128 v[80:83], v76 offset:16384
	ds_read_b128 v[84:87], v76 offset:20480
	ds_read_b128 v[88:91], v76 offset:24576
	ds_read_b128 v[92:95], v76 offset:28672
	v_max3_f32 v68, v96, v97, v98
	v_max3_f32 v70, v104, v105, v106
	v_max3_f32 v71, v112, v113, v114
	v_max3_f32 v72, v120, v121, v122
	v_max3_f32 v68, v68, v99, v100
	v_max3_f32 v70, v70, v107, v108
	v_max3_f32 v71, v71, v115, v116
	v_max3_f32 v72, v72, v123, v124
	s_waitcnt lgkmcnt(3)
	v_mfma_f32_32x32x16_bf16 v[0:15], v[80:83], v[64:67], v[0:15]
	v_max3_f32 v68, v68, v101, v102
	v_max3_f32 v70, v70, v109, v110
	v_max3_f32 v71, v71, v117, v118
	v_max3_f32 v72, v72, v125, v126
	s_xor_b32 s34, s33, 0x10000
	v_max3_f32 v68, v68, v103, v70
	v_max3_f32 v70, v71, v119, v72
	s_waitcnt lgkmcnt(2)
	v_mfma_f32_32x32x16_bf16 v[48:63], v[84:87], v[64:67], v[48:63]
	v_max3_f32 v68, v68, v111, v127
	v_max3_f32 v68, v68, v70, v70
	v_mov_b32_e32 v70, v68
	s_nop 1
	v_permlane32_swap_b32_e32 v68, v70
	v_max3_f32 v68, v68, v70, v70
	v_max_f32_e32 v141, v214, v68
	s_waitcnt lgkmcnt(1)
	v_mfma_f32_32x32x16_bf16 v[32:47], v[88:91], v[64:67], v[32:47]
	v_sub_f32_e32 v70, v214, v141
	v_exp_f32_e32 v140, v70
	v_add_f32_e32 v70, 0x41000000, v214
	v_cmp_gt_f32_e32 vcc, v68, v70
	s_cmp_eq_u64 vcc, 0
	v_mul_f32_e32 v68, v69, v140
	s_cselect_b64 s[0:1], -1, 0
	v_cndmask_b32_e64 v194, v68, v69, s[0:1]
	s_waitcnt lgkmcnt(0)
	v_mfma_f32_32x32x16_bf16 v[16:31], v[92:95], v[64:67], v[16:31]
	v_add_u32_e32 v182, s33, v237
	v_add_u32_e32 v158, s34, v236
	v_add_u32_e32 v88, v158, v233
	v_add_u32_e32 v150, v182, v233
	v_add_u32_e32 v159, v158, v232
	v_cndmask_b32_e64 v214, v141, v214, s[0:1]
	v_add_u32_e32 v141, v182, v232
	v_sub_f32_e32 v180, v102, v214
	v_sub_f32_e32 v181, v103, v214
	v_sub_f32_e32 v116, v116, v214
	v_sub_f32_e32 v117, v117, v214
	v_sub_f32_e32 v108, v108, v214
	v_sub_f32_e32 v109, v109, v214
	v_sub_f32_e32 v124, v124, v214
	v_sub_f32_e32 v125, v125, v214
	v_exp_f32_e32 v116, v116
	v_exp_f32_e32 v117, v117
	v_exp_f32_e32 v108, v108
	v_exp_f32_e32 v124, v124
	v_exp_f32_e32 v109, v109
	v_add_u32_e32 v68, v158, v230
	v_add_u32_e32 v158, v158, v231
	v_exp_f32_e32 v125, v125
	v_sub_f32_e32 v114, v114, v214
	v_sub_f32_e32 v115, v115, v214
	v_sub_f32_e32 v118, v118, v214
	v_sub_f32_e32 v119, v119, v214
	v_sub_f32_e32 v122, v122, v214
	v_sub_f32_e32 v123, v123, v214
	v_sub_f32_e32 v110, v110, v214
	v_sub_f32_e32 v111, v111, v214
	ds_read_b128 v[64:67], v68
	ds_read_b128 v[80:83], v68 offset:4096
	ds_read_b128 v[84:87], v88
	ds_read_b128 v[142:145], v88 offset:4096
	v_sub_f32_e32 v126, v126, v214
	v_sub_f32_e32 v127, v127, v214
	v_sub_f32_e32 v106, v106, v214
	v_sub_f32_e32 v107, v107, v214
	v_exp_f32_e32 v114, v114
	v_exp_f32_e32 v115, v115
	v_exp_f32_e32 v118, v118
	s_waitcnt lgkmcnt(0)
	v_mfma_f32_32x32x16_bf16 v[64:79], v[64:67], v[160:163], 0
	v_exp_f32_e32 v119, v119
	v_exp_f32_e32 v122, v122
	v_exp_f32_e32 v123, v123
	v_exp_f32_e32 v110, v110
	v_exp_f32_e32 v126, v126
	v_exp_f32_e32 v111, v111
	v_exp_f32_e32 v127, v127
	v_mfma_f32_32x32x16_bf16 v[64:79], v[84:87], v[164:167], v[64:79]
	v_sub_f32_e32 v104, v104, v214
	v_sub_f32_e32 v105, v105, v214
	v_sub_f32_e32 v112, v112, v214
	v_sub_f32_e32 v113, v113, v214
	v_sub_f32_e32 v120, v120, v214
	v_sub_f32_e32 v121, v121, v214
	v_cvt_pk_bf16_f32 v183, v118, v119
	v_exp_f32_e32 v112, v112
	v_exp_f32_e32 v113, v113
	v_exp_f32_e32 v120, v120
	v_mfma_f32_32x32x16_bf16 v[80:95], v[80:83], v[160:163], 0
	v_exp_f32_e32 v121, v121
	v_cvt_pk_bf16_f32 v186, v108, v109
	v_cvt_pk_bf16_f32 v187, v110, v111
	v_mfma_f32_32x32x16_bf16 v[80:95], v[142:145], v[164:167], v[80:95]
	ds_read_b128 v[142:145], v150 offset:16384
	ds_read_b128 v[146:149], v150 offset:20480
	s_waitcnt lgkmcnt(0)
	v_mfma_f32_32x32x16_bf16 v[0:15], v[142:145], v[136:139], v[0:15]
	ds_read_b128 v[142:145], v150 offset:24576
	ds_read_b128 v[150:153], v150 offset:28672
	ds_read_b128 v[154:157], v159
	ds_read_b128 v[176:179], v159 offset:4096
	v_mfma_f32_32x32x16_bf16 v[48:63], v[146:149], v[136:139], v[48:63]
	ds_read_b128 v[146:149], v158
	ds_read_b128 v[238:241], v158 offset:4096
	v_sub_f32_e32 v158, v96, v214
	v_sub_f32_e32 v159, v97, v214
	s_waitcnt lgkmcnt(0)
	v_mfma_f32_32x32x16_bf16 v[32:47], v[142:145], v[136:139], v[32:47]
	v_sub_f32_e32 v142, v98, v214
	v_sub_f32_e32 v143, v99, v214
	v_sub_f32_e32 v144, v100, v214
	v_sub_f32_e32 v145, v101, v214
	ds_read_b128 v[96:99], v141 offset:16384
	ds_read_b128 v[100:103], v141 offset:20480
	s_waitcnt lgkmcnt(0)
	v_mfma_f32_32x32x16_bf16 v[0:15], v[96:99], v[132:135], v[0:15]
	ds_read_b128 v[96:99], v141 offset:24576
	v_mfma_f32_32x32x16_bf16 v[48:63], v[100:103], v[132:135], v[48:63]
	ds_read_b128 v[100:103], v141 offset:28672
	v_add_u32_e32 v141, v182, v231
	v_cvt_pk_bf16_f32 v182, v116, v117
	v_mfma_f32_32x32x16_bf16 v[16:31], v[150:153], v[136:139], v[16:31]
	v_exp_f32_e32 v138, v142
	v_exp_f32_e32 v139, v143
	v_exp_f32_e32 v142, v144
	v_exp_f32_e32 v143, v145
	v_exp_f32_e32 v144, v180
	v_exp_f32_e32 v145, v181
	v_exp_f32_e32 v136, v158
	s_waitcnt lgkmcnt(0)
	v_mfma_f32_32x32x16_bf16 v[32:47], v[96:99], v[132:135], v[32:47]
	ds_read_b128 v[96:99], v141 offset:16384
	v_exp_f32_e32 v137, v159
	v_cvt_pk_bf16_f32 v180, v112, v113
	v_cvt_pk_bf16_f32 v181, v114, v115
	v_add_f32_e32 v152, v136, v112
	v_add_f32_e32 v153, v137, v113
	v_mfma_f32_32x32x16_bf16 v[16:31], v[100:103], v[132:135], v[16:31]
	v_add_f32_e64 v100, v108, v124
	v_add_f32_e64 v101, v109, v125
	v_add_f32_e64 v102, v142, v116
	v_add_f32_e64 v103, v143, v117
	v_exp_f32_e32 v134, v106
	v_exp_f32_e32 v135, v107
	v_exp_f32_e32 v132, v104
	v_exp_f32_e32 v133, v105
	v_add_f32_e32 v106, v138, v114
	v_add_f32_e32 v107, v139, v115
	v_mfma_f32_32x32x16_bf16 v[64:79], v[154:157], v[168:171], v[64:79]
	v_add_f32_e64 v154, v102, v100
	v_add_f32_e64 v155, v103, v101
	ds_read_b128 v[100:103], v141 offset:20480
	v_add_f32_e64 v104, v134, v122
	v_add_f32_e64 v105, v135, v123
	v_add_f32_e32 v150, v132, v120
	v_add_f32_e32 v151, v133, v121
	v_add_f32_e32 v104, v106, v104
	v_add_f32_e32 v105, v107, v105
	v_cvt_pk_bf16_f32 v184, v132, v133
	v_cvt_pk_bf16_f32 v185, v134, v135
	v_mfma_f32_32x32x16_bf16 v[64:79], v[146:149], v[172:175], v[64:79]
	v_add_f32_e64 v146, v110, v126
	v_add_f32_e64 v147, v111, v127
	v_add_f32_e64 v148, v144, v118
	v_add_f32_e64 v149, v145, v119
	s_waitcnt lgkmcnt(0)
	v_mfma_f32_32x32x16_bf16 v[0:15], v[96:99], v[128:131], v[0:15]
	v_add_f32_e64 v98, v148, v146
	v_add_f32_e64 v99, v149, v147
	v_add_f32_e64 v96, v152, v150
	v_add_f32_e64 v97, v153, v151
	v_add_f32_e64 v98, v104, v98
	v_add_f32_e64 v99, v105, v99
	ds_read_b128 v[104:107], v141 offset:24576
	v_add_f32_e32 v96, v96, v154
	v_add_f32_e32 v97, v97, v155
	s_nop 0
	v_add_f32_e32 v96, v96, v97
	v_mfma_f32_32x32x16_bf16 v[48:63], v[100:103], v[128:131], v[48:63]
	ds_read_b128 v[100:103], v141 offset:28672
	v_add_f32_e32 v97, v98, v99
	v_add_f32_e32 v146, v96, v97
	v_cvt_pk_bf16_f32 v96, v136, v137
	v_cvt_pk_bf16_f32 v97, v138, v139
	v_cvt_pk_bf16_f32 v98, v142, v143
	v_cvt_pk_bf16_f32 v99, v144, v145
	v_mfma_f32_32x32x16_bf16 v[80:95], v[176:179], v[168:171], v[80:95]
	v_cvt_pk_bf16_f32 v176, v120, v121
	v_cvt_pk_bf16_f32 v177, v122, v123
	v_cvt_pk_bf16_f32 v178, v124, v125
	v_cvt_pk_bf16_f32 v179, v126, v127
	s_waitcnt lgkmcnt(0)
	v_mfma_f32_32x32x16_bf16 v[32:47], v[104:107], v[128:131], v[32:47]
	v_mfma_f32_32x32x16_bf16 v[16:31], v[100:103], v[128:131], v[16:31]
	v_add_f32_e32 v100, v194, v146
	v_mfma_f32_32x32x16_bf16 v[80:95], v[238:241], v[172:175], v[80:95]
	s_cbranch_vccz .LBB0_872
	v_pk_mul_f32 v[14:15], v[140:141], v[14:15] op_sel_hi:[0,1]
	v_pk_mul_f32 v[12:13], v[140:141], v[12:13] op_sel_hi:[0,1]
	v_pk_mul_f32 v[10:11], v[140:141], v[10:11] op_sel_hi:[0,1]
	v_pk_mul_f32 v[8:9], v[140:141], v[8:9] op_sel_hi:[0,1]
	v_pk_mul_f32 v[6:7], v[140:141], v[6:7] op_sel_hi:[0,1]
	v_pk_mul_f32 v[4:5], v[140:141], v[4:5] op_sel_hi:[0,1]
	v_pk_mul_f32 v[2:3], v[140:141], v[2:3] op_sel_hi:[0,1]
	v_pk_mul_f32 v[0:1], v[140:141], v[0:1] op_sel_hi:[0,1]
	v_pk_mul_f32 v[62:63], v[140:141], v[62:63] op_sel_hi:[0,1]
	v_pk_mul_f32 v[60:61], v[140:141], v[60:61] op_sel_hi:[0,1]
	v_pk_mul_f32 v[58:59], v[140:141], v[58:59] op_sel_hi:[0,1]
	v_pk_mul_f32 v[56:57], v[140:141], v[56:57] op_sel_hi:[0,1]
	v_pk_mul_f32 v[54:55], v[140:141], v[54:55] op_sel_hi:[0,1]
	v_pk_mul_f32 v[52:53], v[140:141], v[52:53] op_sel_hi:[0,1]
	v_pk_mul_f32 v[50:51], v[140:141], v[50:51] op_sel_hi:[0,1]
	v_pk_mul_f32 v[48:49], v[140:141], v[48:49] op_sel_hi:[0,1]
	v_pk_mul_f32 v[46:47], v[140:141], v[46:47] op_sel_hi:[0,1]
	v_pk_mul_f32 v[44:45], v[140:141], v[44:45] op_sel_hi:[0,1]
	v_pk_mul_f32 v[42:43], v[140:141], v[42:43] op_sel_hi:[0,1]
	v_pk_mul_f32 v[40:41], v[140:141], v[40:41] op_sel_hi:[0,1]
	v_pk_mul_f32 v[38:39], v[140:141], v[38:39] op_sel_hi:[0,1]
	v_pk_mul_f32 v[36:37], v[140:141], v[36:37] op_sel_hi:[0,1]
	v_pk_mul_f32 v[34:35], v[140:141], v[34:35] op_sel_hi:[0,1]
	v_pk_mul_f32 v[32:33], v[140:141], v[32:33] op_sel_hi:[0,1]
	v_pk_mul_f32 v[30:31], v[140:141], v[30:31] op_sel_hi:[0,1]
	v_pk_mul_f32 v[28:29], v[140:141], v[28:29] op_sel_hi:[0,1]
	v_pk_mul_f32 v[26:27], v[140:141], v[26:27] op_sel_hi:[0,1]
	v_pk_mul_f32 v[24:25], v[140:141], v[24:25] op_sel_hi:[0,1]
	v_pk_mul_f32 v[22:23], v[140:141], v[22:23] op_sel_hi:[0,1]
	v_pk_mul_f32 v[20:21], v[140:141], v[20:21] op_sel_hi:[0,1]
	v_pk_mul_f32 v[18:19], v[140:141], v[18:19] op_sel_hi:[0,1]
	v_pk_mul_f32 v[16:17], v[140:141], v[16:17] op_sel_hi:[0,1]
